# v148 + column-sum loads together + row-sum prefetch + widened attention epilogue stores + lead waves issue the in-loop K/V DMA
# speedup vs baseline: 1.0417x; 1.0011x over previous
; #define ATT_DMAK(t) do { const int sl_ = (t) % NSLOT; _Pragma("unroll") for (int i = 0; i < 2; ++i) \
;         __builtin_amdgcn_global_load_lds((const unsigned*)(Kg + (size_t)(t) * 16384 + i * 1024), (LAS unsigned*)(lds + OFF_K + sl_ * KBUF + wid * 2048 + i * 1024), 16, 0, 0); } while (0)
; #define ATT_DMAV(t) do { const int sl_ = (t) % NSLOT; _Pragma("unroll") for (int i = 0; i < 2; ++i) \
;         __builtin_amdgcn_global_load_lds((const unsigned*)(Vg + (size_t)(t) * 16384 + i * 1024), (LAS unsigned*)(lds + OFF_V + sl_ * VBUF + wid * 2048 + i * 1024), 16, 0, 0); } while (0)
; __device__ __forceinline__ void attn_unit(LAS unsigned char* lds, int b, int hh, int qb, const bf16_t* QK, const bf16_t* VT, bf16_t* CAT) {
;     ...
;         if (t + 2 < nt) ATT_DMAK(t + 2);
;         if (t + 1 < nt) ATT_DMAV(t + 1);
.LBB0_248:
	s_cmp_ge_u32 s26, s48
	s_cselect_b64 s[12:13], -1, 0
	s_and_b64 vcc, exec, s[12:13]
	s_cbranch_vccnz .LBB0_250
	s_and_b64 vcc, exec, s[4:5]
	s_cbranch_vccnz .LBB0_250
	s_mul_hi_u32 s14, s26, 0xaaaaaaab
	s_lshr_b32 s14, s14, 1
	s_mul_i32 s14, s14, 0xc000
	s_sub_i32 s14, s53, s14
	v_lshl_add_u64 v[2:3], v[164:165], 0, s[2:3]
	s_add_i32 s14, s14, s46
	v_lshl_add_u64 v[4:5], v[2:3], 0, s[78:79]
	s_add_i32 m0, s14, 0x8000
	v_lshl_add_u64 v[2:3], v[2:3], 0, s[80:81]
	global_load_lds_dwordx4 v[4:5], off
	s_add_i32 m0, s14, 0x8400
	s_nop 0
	global_load_lds_dwordx4 v[2:3], off
	v_add_co_u32_e32 v4, vcc, 0x2000, v4
	v_addc_co_u32_e32 v5, vcc, 0, v5, vcc
	s_add_i32 m0, s14, 0xa000
	s_nop 0
	global_load_lds_dwordx4 v[4:5], off
	v_add_co_u32_e32 v2, vcc, 0x2000, v2
	v_addc_co_u32_e32 v3, vcc, 0, v3, vcc
	s_add_i32 m0, s14, 0xa400
	s_nop 0
	global_load_lds_dwordx4 v[2:3], off
.LBB0_250:
	s_add_i32 s14, s26, -1
	s_cmp_ge_u32 s14, s48
	s_cbranch_scc1 .LBB0_252
	s_and_b64 vcc, exec, s[4:5]
	s_cbranch_vccnz .LBB0_252
	s_mul_hi_u32 s14, s1, 0xaaaaaaab
	s_lshr_b32 s14, s14, 1
	s_mul_i32 s14, s14, 0xc000
	s_sub_i32 s14, s53, s14
	v_lshl_add_u64 v[2:3], v[176:177], 0, s[2:3]
	s_add_i32 s14, s14, s46
	v_lshl_add_u64 v[4:5], v[2:3], 0, s[82:83]
	s_add_i32 m0, s14, 0x10000
	v_lshl_add_u64 v[2:3], v[2:3], 0, s[84:85]
	global_load_lds_dwordx4 v[4:5], off
	s_add_i32 m0, s14, 0x10400
	s_nop 0
	global_load_lds_dwordx4 v[2:3], off
	v_add_co_u32_e32 v4, vcc, 0x2000, v4
	v_addc_co_u32_e32 v5, vcc, 0, v5, vcc
	s_add_i32 m0, s14, 0x12000
	s_nop 0
	global_load_lds_dwordx4 v[4:5], off
	v_add_co_u32_e32 v2, vcc, 0x2000, v2
	v_addc_co_u32_e32 v3, vcc, 0, v3, vcc
	s_add_i32 m0, s14, 0x12400
	s_nop 0
	global_load_lds_dwordx4 v[2:3], off

; __device__ __forceinline__ void attn_unit(LAS unsigned char* lds, int b, int hh, int qb, const bf16_t* QK, const bf16_t* VT, bf16_t* CAT) {
;     ...
;         if (t + 2 < nt) asm volatile("s_waitcnt vmcnt(4) lgkmcnt(0)" ::: "memory"); else asm volatile("s_waitcnt vmcnt(0) lgkmcnt(0)" ::: "memory");
.LBB0_316:
	s_andn2_b64 vcc, exec, s[14:15]
	s_cbranch_vccnz .LBB0_247
	s_waitcnt vmcnt(8) lgkmcnt(0)
	s_branch .LBB0_247

; #define ATT_DMAK(t) do { const int sl_ = (t) % NSLOT; _Pragma("unroll") for (int i = 0; i < 2; ++i) \
;         __builtin_amdgcn_global_load_lds((const unsigned*)(Kg + (size_t)(t) * 16384 + i * 1024), (LAS unsigned*)(lds + OFF_K + sl_ * KBUF + wid * 2048 + i * 1024), 16, 0, 0); } while (0)
; #define ATT_DMAV(t) do { const int sl_ = (t) % NSLOT; _Pragma("unroll") for (int i = 0; i < 2; ++i) \
;         __builtin_amdgcn_global_load_lds((const unsigned*)(Vg + (size_t)(t) * 16384 + i * 1024), (LAS unsigned*)(lds + OFF_V + sl_ * VBUF + wid * 2048 + i * 1024), 16, 0, 0); } while (0)
; __device__ __forceinline__ void attn_unit(LAS unsigned char* lds, int b, int hh, int qb, const bf16_t* QK, const bf16_t* VT, bf16_t* CAT) {
;     ...
;         if (t + 2 < nt) ATT_DMAK(t + 2);
;         if (t + 1 < nt) ATT_DMAV(t + 1);
.LBB0_320:
	s_add_i32 s12, s67, 2
	s_cmp_ge_u32 s12, s58
	s_cselect_b64 s[12:13], -1, 0
	s_and_b64 vcc, exec, s[12:13]
	s_cbranch_vccnz .LBB0_322
	s_and_b64 vcc, exec, s[4:5]
	s_cbranch_vccnz .LBB0_322
	s_mul_hi_u32 s14, s51, 0xaaaaaaab
	s_lshr_b32 s14, s14, 1
	s_mul_i32 s14, s14, 0xc000
	s_sub_i32 s14, s48, s14
	v_lshl_add_u64 v[2:3], v[164:165], 0, s[2:3]
	s_add_i32 s14, s14, s53
	v_lshl_add_u64 v[4:5], v[2:3], 0, s[78:79]
	s_add_i32 m0, s14, 0x8000
	v_lshl_add_u64 v[2:3], v[2:3], 0, s[80:81]
	global_load_lds_dwordx4 v[4:5], off
	s_add_i32 m0, s14, 0x8400
	s_nop 0
	global_load_lds_dwordx4 v[2:3], off
	v_add_co_u32_e32 v4, vcc, 0x2000, v4
	v_addc_co_u32_e32 v5, vcc, 0, v5, vcc
	s_add_i32 m0, s14, 0xa000
	s_nop 0
	global_load_lds_dwordx4 v[4:5], off
	v_add_co_u32_e32 v2, vcc, 0x2000, v2
	v_addc_co_u32_e32 v3, vcc, 0, v3, vcc
	s_add_i32 m0, s14, 0xa400
	s_nop 0
	global_load_lds_dwordx4 v[2:3], off
.LBB0_322:
	s_add_i32 s66, s67, 1
	s_cmp_ge_u32 s66, s58
	s_cbranch_scc1 .LBB0_324
	s_and_b64 vcc, exec, s[4:5]
	s_cbranch_vccnz .LBB0_324
	s_mul_hi_u32 s14, s59, 0xaaaaaaab
	s_lshr_b32 s14, s14, 1
	s_mul_i32 s14, s14, 0xc000
	s_sub_i32 s14, s48, s14
	v_lshl_add_u64 v[2:3], v[176:177], 0, s[2:3]
	s_add_i32 s14, s14, s53
	v_lshl_add_u64 v[4:5], v[2:3], 0, s[82:83]
	s_add_i32 m0, s14, 0x10000
	v_lshl_add_u64 v[2:3], v[2:3], 0, s[84:85]
	global_load_lds_dwordx4 v[4:5], off
	s_add_i32 m0, s14, 0x10400
	s_nop 0
	global_load_lds_dwordx4 v[2:3], off
	v_add_co_u32_e32 v4, vcc, 0x2000, v4
	v_addc_co_u32_e32 v5, vcc, 0, v5, vcc
	s_add_i32 m0, s14, 0x12000
	s_nop 0
	global_load_lds_dwordx4 v[4:5], off
	v_add_co_u32_e32 v2, vcc, 0x2000, v2
	v_addc_co_u32_e32 v3, vcc, 0, v3, vcc
	s_add_i32 m0, s14, 0x12400
	s_nop 0
	global_load_lds_dwordx4 v[2:3], off

; __device__ __forceinline__ void attn_unit(LAS unsigned char* lds, int b, int hh, int qb, const bf16_t* QK, const bf16_t* VT, bf16_t* CAT) {
;     ...
;         if (t + 2 < nt) asm volatile("s_waitcnt vmcnt(4) lgkmcnt(0)" ::: "memory"); else asm volatile("s_waitcnt vmcnt(0) lgkmcnt(0)" ::: "memory");
.LBB0_388:
	s_andn2_b64 vcc, exec, s[14:15]
	s_cbranch_vccnz .LBB0_390
	s_waitcnt vmcnt(8) lgkmcnt(0)

; #define ATT_DMAK(t) do { const int sl_ = (t) % NSLOT; _Pragma("unroll") for (int i = 0; i < 2; ++i) \
;         __builtin_amdgcn_global_load_lds((const unsigned*)(Kg + (size_t)(t) * 16384 + i * 1024), (LAS unsigned*)(lds + OFF_K + sl_ * KBUF + wid * 2048 + i * 1024), 16, 0, 0); } while (0)
; #define ATT_DMAV(t) do { const int sl_ = (t) % NSLOT; _Pragma("unroll") for (int i = 0; i < 2; ++i) \
;         __builtin_amdgcn_global_load_lds((const unsigned*)(Vg + (size_t)(t) * 16384 + i * 1024), (LAS unsigned*)(lds + OFF_V + sl_ * VBUF + wid * 2048 + i * 1024), 16, 0, 0); } while (0)
; __device__ __forceinline__ void attn_unit(LAS unsigned char* lds, int b, int hh, int qb, const bf16_t* QK, const bf16_t* VT, bf16_t* CAT) {
;     ...
;         if (t + 2 < nt) ATT_DMAK(t + 2);
;         if (t + 1 < nt) ATT_DMAV(t + 1);
.LBB0_395:
	s_cmp_ge_u32 s51, s53
	s_cselect_b64 s[12:13], -1, 0
	s_and_b64 vcc, exec, s[12:13]
	s_cbranch_vccnz .LBB0_397
	s_and_b64 vcc, exec, s[4:5]
	s_cbranch_vccnz .LBB0_397
	s_mul_hi_u32 s14, s51, 0xaaaaaaab
	s_lshr_b32 s14, s14, 1
	s_mul_i32 s14, s14, 0xc000
	s_sub_i32 s14, s1, s14
	v_lshl_add_u64 v[2:3], v[164:165], 0, s[2:3]
	s_add_i32 s14, s14, s52
	v_lshl_add_u64 v[4:5], v[2:3], 0, s[78:79]
	s_add_i32 m0, s14, 0x8000
	v_lshl_add_u64 v[2:3], v[2:3], 0, s[80:81]
	global_load_lds_dwordx4 v[4:5], off
	s_add_i32 m0, s14, 0x8400
	s_nop 0
	global_load_lds_dwordx4 v[2:3], off
	v_add_co_u32_e32 v4, vcc, 0x2000, v4
	v_addc_co_u32_e32 v5, vcc, 0, v5, vcc
	s_add_i32 m0, s14, 0xa000
	s_nop 0
	global_load_lds_dwordx4 v[4:5], off
	v_add_co_u32_e32 v2, vcc, 0x2000, v2
	v_addc_co_u32_e32 v3, vcc, 0, v3, vcc
	s_add_i32 m0, s14, 0xa400
	s_nop 0
	global_load_lds_dwordx4 v[2:3], off
.LBB0_397:
	s_add_i32 s14, s51, -1
	s_cmp_ge_u32 s14, s53
	s_cbranch_scc1 .LBB0_399
	s_and_b64 vcc, exec, s[4:5]
	s_cbranch_vccnz .LBB0_399
	s_mul_hi_u32 s14, s48, 0xaaaaaaab
	s_lshr_b32 s14, s14, 1
	s_mul_i32 s14, s14, 0xc000
	s_sub_i32 s14, s1, s14
	v_lshl_add_u64 v[2:3], v[176:177], 0, s[2:3]
	s_add_i32 s14, s14, s52
	v_lshl_add_u64 v[4:5], v[2:3], 0, s[82:83]
	s_add_i32 m0, s14, 0x10000
	v_lshl_add_u64 v[2:3], v[2:3], 0, s[84:85]
	global_load_lds_dwordx4 v[4:5], off
	s_add_i32 m0, s14, 0x10400
	s_nop 0
	global_load_lds_dwordx4 v[2:3], off
	v_add_co_u32_e32 v4, vcc, 0x2000, v4
	v_addc_co_u32_e32 v5, vcc, 0, v5, vcc
	s_add_i32 m0, s14, 0x12000
	s_nop 0
	global_load_lds_dwordx4 v[4:5], off
	v_add_co_u32_e32 v2, vcc, 0x2000, v2
	v_addc_co_u32_e32 v3, vcc, 0, v3, vcc
	s_add_i32 m0, s14, 0x12400
	s_nop 0
	global_load_lds_dwordx4 v[2:3], off

; #define ATT_DMAK(t) do { const int sl_ = (t) % NSLOT; _Pragma("unroll") for (int i = 0; i < 2; ++i) \
;         __builtin_amdgcn_global_load_lds((const unsigned*)(Kg + (size_t)(t) * 16384 + i * 1024), (LAS unsigned*)(lds + OFF_K + sl_ * KBUF + wid * 2048 + i * 1024), 16, 0, 0); } while (0)
; #define ATT_DMAV(t) do { const int sl_ = (t) % NSLOT; _Pragma("unroll") for (int i = 0; i < 2; ++i) \
;         __builtin_amdgcn_global_load_lds((const unsigned*)(Vg + (size_t)(t) * 16384 + i * 1024), (LAS unsigned*)(lds + OFF_V + sl_ * VBUF + wid * 2048 + i * 1024), 16, 0, 0); } while (0)
; __device__ __forceinline__ void attn_unit(LAS unsigned char* lds, int b, int hh, int qb, const bf16_t* QK, const bf16_t* VT, bf16_t* CAT) {
;     ...
;         if (t + 2 < nt) ATT_DMAK(t + 2);
;         if (t + 1 < nt) ATT_DMAV(t + 1);
.LBB0_468:
	s_cmp_ge_u32 s46, s23
	s_cselect_b64 s[12:13], -1, 0
	s_and_b64 vcc, exec, s[12:13]
	s_cbranch_vccnz .LBB0_470
	s_and_b64 vcc, exec, s[4:5]
	s_cbranch_vccnz .LBB0_470
	s_mul_hi_u32 s14, s46, 0xaaaaaaab
	s_lshr_b32 s14, s14, 1
	s_mul_i32 s14, s14, 0xc000
	s_sub_i32 s14, s48, s14
	v_lshl_add_u64 v[152:153], v[148:149], 0, s[2:3]
	s_add_i32 s14, s14, s22
	v_lshl_add_u64 v[154:155], v[152:153], 0, s[78:79]
	s_add_i32 m0, s14, 0x8000
	v_lshl_add_u64 v[152:153], v[152:153], 0, s[80:81]
	global_load_lds_dwordx4 v[154:155], off
	s_add_i32 m0, s14, 0x8400
	s_nop 0
	global_load_lds_dwordx4 v[152:153], off
	v_add_co_u32_e32 v154, vcc, 0x2000, v154
	v_addc_co_u32_e32 v155, vcc, 0, v155, vcc
	s_add_i32 m0, s14, 0xa000
	s_nop 0
	global_load_lds_dwordx4 v[154:155], off
	v_add_co_u32_e32 v152, vcc, 0x2000, v152
	v_addc_co_u32_e32 v153, vcc, 0, v153, vcc
	s_add_i32 m0, s14, 0xa400
	s_nop 0
	global_load_lds_dwordx4 v[152:153], off
.LBB0_470:
	s_add_i32 s14, s46, -1
	s_cmp_ge_u32 s14, s23
	s_cbranch_scc1 .LBB0_472
	s_and_b64 vcc, exec, s[4:5]
	s_cbranch_vccnz .LBB0_472
	s_mul_hi_u32 s14, s1, 0xaaaaaaab
	s_lshr_b32 s14, s14, 1
	s_mul_i32 s14, s14, 0xc000
	s_sub_i32 s14, s48, s14
	v_lshl_add_u64 v[152:153], v[150:151], 0, s[2:3]
	s_add_i32 s14, s14, s22
	v_lshl_add_u64 v[154:155], v[152:153], 0, s[82:83]
	s_add_i32 m0, s14, 0x10000
	v_lshl_add_u64 v[152:153], v[152:153], 0, s[84:85]
	global_load_lds_dwordx4 v[154:155], off
	s_add_i32 m0, s14, 0x10400
	s_nop 0
	global_load_lds_dwordx4 v[152:153], off
	v_add_co_u32_e32 v154, vcc, 0x2000, v154
	v_addc_co_u32_e32 v155, vcc, 0, v155, vcc
	s_add_i32 m0, s14, 0x12000
	s_nop 0
	global_load_lds_dwordx4 v[154:155], off
	v_add_co_u32_e32 v152, vcc, 0x2000, v152
	v_addc_co_u32_e32 v153, vcc, 0, v153, vcc
	s_add_i32 m0, s14, 0x12400
	s_nop 0
	global_load_lds_dwordx4 v[152:153], off
